# fully XCD-decoupled pipeline after the P0 barrier, 12us XCD-group stagger moved to P1 start so it persists through every phase
# speedup vs baseline: 1.0012x; 1.0008x over previous
.LBB0_126:
	s_mov_b32 s99, 0
	s_cmp_lg_u32 s3, 0x100
	s_cbranch_scc1 .Lflag_done
	v_mbcnt_lo_u32_b32 v0, -1, 0
	v_mbcnt_hi_u32_b32 v0, -1, v0
	v_lshlrev_b32_e32 v1, 4, v0
	v_add_u32_e32 v1, 0xe000, v1
	global_load_dwordx4 v[4:7], v1, s[76:77]
	v_and_b32_e32 v2, 1, v0
	s_waitcnt vmcnt(0)
	v_readlane_b32 s4, v4, 0
	v_readlane_b32 s5, v5, 0
	v_readlane_b32 s6, v6, 0
	v_readlane_b32 s7, v7, 0
	v_readlane_b32 s8, v4, 1
	v_readlane_b32 s9, v5, 1
	v_readlane_b32 s10, v6, 1
	v_readlane_b32 s11, v7, 1
	v_cmp_eq_u32_e32 vcc, 1, v2
	v_mov_b32_e32 v8, s4
	v_mov_b32_e32 v9, s8
	v_cndmask_b32_e32 v8, v8, v9, vcc
	v_mov_b32_e32 v10, s5
	v_mov_b32_e32 v9, s9
	v_cndmask_b32_e32 v10, v10, v9, vcc
	v_mov_b32_e32 v11, s6
	v_mov_b32_e32 v9, s10
	v_cndmask_b32_e32 v11, v11, v9, vcc
	v_mov_b32_e32 v12, s7
	v_mov_b32_e32 v9, s11
	v_cndmask_b32_e32 v12, v12, v9, vcc
	v_xor_b32_e32 v8, v4, v8
	v_xor_b32_e32 v10, v5, v10
	v_xor_b32_e32 v11, v6, v11
	v_xor_b32_e32 v12, v7, v12
	v_or3_b32 v8, v8, v10, v11
	v_or_b32_e32 v8, v8, v12
	v_min_u32_e32 v9, v4, v5
	v_min3_u32 v9, v9, v6, v7
	v_cmp_ne_u32_e32 vcc, 0, v8
	v_cmp_eq_u32_e64 s[4:5], 0, v9
	s_nop 3
	s_or_b64 s[4:5], vcc, s[4:5]
	s_cmp_lg_u64 s[4:5], 0
	s_cbranch_scc1 .Lflag_done
	s_mov_b32 s99, 1
.Lflag_done:
	s_cmp_eq_u32 s99, 0
	s_cbranch_scc1 .Lstag1_done
	s_bitcmp1_b32 s2, 2
	s_cbranch_scc0 .Lstag1_done
	s_sleep 127
	s_sleep 127
	s_sleep 127
.Lstag1_done:
	s_cmp_lt_i32 s27, 0
	s_cselect_b64 s[4:5], -1, 0
	s_cmp_gt_i32 s27, -1
	s_cselect_b64 s[0:1], -1, 0
	s_add_u32 s40, s76, 0x7c00000
	s_addc_u32 s41, s77, 0
	s_cmp_lg_u32 s27, 1
	s_cselect_b64 s[6:7], -1, 0
	s_and_b64 s[0:1], s[0:1], s[6:7]
	s_and_b64 vcc, exec, s[0:1]
	s_cbranch_vccnz .LBB0_256
	v_mov_b32_e32 v0, 0
	v_mov_b32_e32 v22, 0
	v_mbcnt_lo_u32_b32 v0, -1, v0
	v_mbcnt_hi_u32_b32 v0, -1, v0
	v_add_u32_e32 v23, s33, v0
	s_cmp_gt_u32 s2, 63
	v_readfirstlane_b32 s8, v23
	s_cbranch_scc1 .LBB0_151
	s_mov_b32 s98, s2
	s_cmp_eq_u32 s99, 0
	s_cbranch_scc1 .Lfs_done
	s_and_b32 s98, s2, 7
	s_lshl_b32 s98, s98, 3
	s_lshr_b32 s100, s2, 3
	s_or_b32 s98, s98, s100

.LBB0_693:
	s_or_b64 exec, exec, s[0:1]
	s_waitcnt lgkmcnt(0)
	s_barrier
.LBB0_694:
	s_cmp_eq_u32 s99, 0
	s_cbranch_scc1 .Lx1b_done
	s_and_b32 s100, s2, 7
	s_mul_i32 s100, s100, 0x2400000
	s_add_u32 s40, s40, s100
	s_addc_u32 s41, s41, 0
